# norm phase: split-K partial slabs of the sample rows are loaded together (one wait) instead of one round trip per slab; same summation order
# speedup vs baseline: 1.0405x; 1.0107x over previous
; __device__ __forceinline__ void phase_norm(PP P, int l, int which, int nsl, const float* fgate, float fscale, const Ids I) {
;     ...
;             if (nsl > 0 && row >= MTP && !(j == 1 && row == row0)) {
;                 const float* pp = (const float*)(P->ws + WS_R2) + (size_t)(row - MTP) * D + lane * 4; const float* gp = fgate + (size_t)mod_row(row) * 9216 + lane * 4;
; #pragma unroll
;                 for (int i = 0; i < 4; ++i) { f32x4 a = (f32x4){0.f, 0.f, 0.f, 0.f};
;                     for (int sl = 0; sl < nsl; ++sl) a += *(const f32x4*)(pp + (size_t)sl * MTS * D + 256 * i);
;                     v[j][i] += (*(const f32x4*)(gp + 256 * i) * fscale) * a;
;                     if (which != 3) *(f32x4*)(xb + (size_t)row * D + lane * 4 + 256 * i) = v[j][i]; } } }
.LBB0_547:
	s_lshl_b64 s[18:19], s[18:19], 12
	s_waitcnt lgkmcnt(0)
	s_add_u32 s4, s4, s18
	s_addc_u32 s5, s5, s19
	v_lshlrev_b32_e32 v144, 2, v48
	global_load_dwordx4 v[20:23], v144, s[4:5]
	global_load_dwordx4 v[12:15], v144, s[4:5] offset:1024
	global_load_dwordx4 v[4:7], v144, s[4:5] offset:2048
	global_load_dwordx4 v[0:3], v144, s[4:5] offset:3072
	s_cmpk_gt_i32 s8, 0x3fff
	s_cselect_b64 s[4:5], -1, 0
	s_and_b64 s[4:5], s[0:1], s[4:5]
	s_andn2_b64 vcc, exec, s[4:5]
	s_cbranch_vccnz .LBB0_557
	s_cmp_eq_u32 s3, 11
	s_cbranch_scc1 .Lnfold11
	s_cmp_eq_u32 s3, 4
	s_cbranch_scc1 .Lnfold4
	s_mov_b32 s17, s55
	s_lshl_b64 s[4:5], s[16:17], 12
	v_mov_b32_e32 v16, 0
	v_lshl_add_u64 v[8:9], v[66:67], 0, s[4:5]
	s_mov_b32 s9, s3
	v_mov_b32_e32 v17, v16
	v_mov_b32_e32 v18, v16
	v_mov_b32_e32 v19, v16

; __device__ __forceinline__ void phase_norm(PP P, int l, int which, int nsl, const float* fgate, float fscale, const Ids I) {
;     ...
;             if (nsl > 0 && row >= MTP && !(j == 1 && row == row0)) {
;                 const float* pp = (const float*)(P->ws + WS_R2) + (size_t)(row - MTP) * D + lane * 4; const float* gp = fgate + (size_t)mod_row(row) * 9216 + lane * 4;
; #pragma unroll
;                 for (int i = 0; i < 4; ++i) { f32x4 a = (f32x4){0.f, 0.f, 0.f, 0.f};
;                     for (int sl = 0; sl < nsl; ++sl) a += *(const f32x4*)(pp + (size_t)sl * MTS * D + 256 * i);
;                     v[j][i] += (*(const f32x4*)(gp + 256 * i) * fscale) * a;
;                     if (which != 3) *(f32x4*)(xb + (size_t)row * D + lane * 4 + 256 * i) = v[j][i]; } } }
.LBB0_555:
	global_load_dwordx4 v[26:29], v[16:17], off
	s_add_i32 s4, s4, -1
	v_lshl_add_u64 v[16:17], v[16:17], 0, s[82:83]
	s_cmp_lg_u32 s4, 0
	s_waitcnt vmcnt(0)
	v_pk_add_f32 v[24:25], v[24:25], v[28:29]
	v_pk_add_f32 v[18:19], v[18:19], v[26:27]
	s_cbranch_scc1 .LBB0_555
	global_load_dwordx4 v[26:29], v[8:9], off offset:3072
	v_mov_b32_e32 v45, v44
	s_waitcnt vmcnt(0)
	v_pk_mul_f32 v[8:9], v[44:45], v[28:29]
	v_pk_mul_f32 v[16:17], v[46:47], v[26:27]
	v_pk_fma_f32 v[2:3], v[24:25], v[8:9], v[2:3]
	v_pk_fma_f32 v[0:1], v[18:19], v[16:17], v[0:1]
	global_store_dwordx4 v[10:11], v[0:3], off offset:3072
	s_branch .LBB0_557
.Lnfold11:
	s_mov_b32 s17, s55
	s_lshl_b64 s[4:5], s[16:17], 12
	s_add_i32 s9, s8, 0xffffc000
	s_lshr_b32 s9, s9, 2
	s_add_i32 s9, s9, 8
	v_mad_u64_u32 v[8:9], s[18:19], s9, v184, v[52:53]
	s_mov_b32 s9, s55
	s_lshl_b64 s[18:19], s[8:9], 12
	v_lshl_add_u64 v[10:11], v[54:55], 0, s[18:19]
	v_lshl_add_u64 v[16:17], v[66:67], 0, s[4:5]
	v_lshl_add_u64 v[24:25], v[68:69], 0, s[4:5]
	global_load_dwordx4 v[158:161], v[8:9], off
	global_load_dwordx4 v[162:165], v[8:9], off offset:1024
	global_load_dwordx4 v[166:169], v[8:9], off offset:2048
	global_load_dwordx4 v[170:173], v[8:9], off offset:3072
	global_load_dwordx4 v[84:87], v[16:17], off
	global_load_dwordx4 v[188:191], v[24:25], off
	v_lshl_add_u64 v[16:17], v[16:17], 0, s[82:83]
	v_lshl_add_u64 v[24:25], v[24:25], 0, s[82:83]
	global_load_dwordx4 v[88:91], v[16:17], off
	global_load_dwordx4 v[192:195], v[24:25], off
	v_lshl_add_u64 v[16:17], v[16:17], 0, s[82:83]
	v_lshl_add_u64 v[24:25], v[24:25], 0, s[82:83]
	global_load_dwordx4 v[92:95], v[16:17], off
	global_load_dwordx4 v[196:199], v[24:25], off
	v_lshl_add_u64 v[16:17], v[16:17], 0, s[82:83]
	v_lshl_add_u64 v[24:25], v[24:25], 0, s[82:83]
	global_load_dwordx4 v[96:99], v[16:17], off
	global_load_dwordx4 v[200:203], v[24:25], off
	v_lshl_add_u64 v[16:17], v[16:17], 0, s[82:83]
	v_lshl_add_u64 v[24:25], v[24:25], 0, s[82:83]
	global_load_dwordx4 v[100:103], v[16:17], off
	global_load_dwordx4 v[204:207], v[24:25], off
	v_lshl_add_u64 v[16:17], v[16:17], 0, s[82:83]
	v_lshl_add_u64 v[24:25], v[24:25], 0, s[82:83]
	global_load_dwordx4 v[104:107], v[16:17], off
	global_load_dwordx4 v[208:211], v[24:25], off
	v_lshl_add_u64 v[16:17], v[16:17], 0, s[82:83]
	v_lshl_add_u64 v[24:25], v[24:25], 0, s[82:83]
	global_load_dwordx4 v[108:111], v[16:17], off
	global_load_dwordx4 v[212:215], v[24:25], off
	v_lshl_add_u64 v[16:17], v[16:17], 0, s[82:83]
	v_lshl_add_u64 v[24:25], v[24:25], 0, s[82:83]
	global_load_dwordx4 v[112:115], v[16:17], off
	global_load_dwordx4 v[216:219], v[24:25], off
	v_lshl_add_u64 v[16:17], v[16:17], 0, s[82:83]
	v_lshl_add_u64 v[24:25], v[24:25], 0, s[82:83]
	global_load_dwordx4 v[116:119], v[16:17], off
	global_load_dwordx4 v[220:223], v[24:25], off
	v_lshl_add_u64 v[16:17], v[16:17], 0, s[82:83]
	v_lshl_add_u64 v[24:25], v[24:25], 0, s[82:83]
	global_load_dwordx4 v[120:123], v[16:17], off
	global_load_dwordx4 v[224:227], v[24:25], off
	v_lshl_add_u64 v[16:17], v[16:17], 0, s[82:83]
	v_lshl_add_u64 v[24:25], v[24:25], 0, s[82:83]
	global_load_dwordx4 v[124:127], v[16:17], off
	global_load_dwordx4 v[228:231], v[24:25], off
	v_mov_b32_e32 v176, 0
	v_mov_b32_e32 v177, 0
	v_mov_b32_e32 v178, 0
	v_mov_b32_e32 v179, 0
	v_mov_b32_e32 v180, 0
	v_mov_b32_e32 v181, 0
	v_mov_b32_e32 v182, 0
	v_mov_b32_e32 v183, 0
	v_mov_b32_e32 v45, v44
	s_waitcnt vmcnt(0)
	v_pk_add_f32 v[178:179], v[178:179], v[86:87]
	v_pk_add_f32 v[176:177], v[176:177], v[84:85]
	v_pk_add_f32 v[182:183], v[182:183], v[190:191]
	v_pk_add_f32 v[180:181], v[180:181], v[188:189]
	v_pk_add_f32 v[178:179], v[178:179], v[90:91]
	v_pk_add_f32 v[176:177], v[176:177], v[88:89]
	v_pk_add_f32 v[182:183], v[182:183], v[194:195]
	v_pk_add_f32 v[180:181], v[180:181], v[192:193]
	v_pk_add_f32 v[178:179], v[178:179], v[94:95]
	v_pk_add_f32 v[176:177], v[176:177], v[92:93]
	v_pk_add_f32 v[182:183], v[182:183], v[198:199]
	v_pk_add_f32 v[180:181], v[180:181], v[196:197]
	v_pk_add_f32 v[178:179], v[178:179], v[98:99]
	v_pk_add_f32 v[176:177], v[176:177], v[96:97]
	v_pk_add_f32 v[182:183], v[182:183], v[202:203]
	v_pk_add_f32 v[180:181], v[180:181], v[200:201]
	v_pk_add_f32 v[178:179], v[178:179], v[102:103]
	v_pk_add_f32 v[176:177], v[176:177], v[100:101]
	v_pk_add_f32 v[182:183], v[182:183], v[206:207]
	v_pk_add_f32 v[180:181], v[180:181], v[204:205]
	v_pk_add_f32 v[178:179], v[178:179], v[106:107]
	v_pk_add_f32 v[176:177], v[176:177], v[104:105]
	v_pk_add_f32 v[182:183], v[182:183], v[210:211]
	v_pk_add_f32 v[180:181], v[180:181], v[208:209]
	v_pk_add_f32 v[178:179], v[178:179], v[110:111]
	v_pk_add_f32 v[176:177], v[176:177], v[108:109]
	v_pk_add_f32 v[182:183], v[182:183], v[214:215]
	v_pk_add_f32 v[180:181], v[180:181], v[212:213]
	v_pk_add_f32 v[178:179], v[178:179], v[114:115]
	v_pk_add_f32 v[176:177], v[176:177], v[112:113]
	v_pk_add_f32 v[182:183], v[182:183], v[218:219]
	v_pk_add_f32 v[180:181], v[180:181], v[216:217]
	v_pk_add_f32 v[178:179], v[178:179], v[118:119]
	v_pk_add_f32 v[176:177], v[176:177], v[116:117]
	v_pk_add_f32 v[182:183], v[182:183], v[222:223]
	v_pk_add_f32 v[180:181], v[180:181], v[220:221]
	v_pk_add_f32 v[178:179], v[178:179], v[122:123]
	v_pk_add_f32 v[176:177], v[176:177], v[120:121]
	v_pk_add_f32 v[182:183], v[182:183], v[226:227]
	v_pk_add_f32 v[180:181], v[180:181], v[224:225]
	v_pk_add_f32 v[178:179], v[178:179], v[126:127]
	v_pk_add_f32 v[176:177], v[176:177], v[124:125]
	v_pk_add_f32 v[182:183], v[182:183], v[230:231]
	v_pk_add_f32 v[180:181], v[180:181], v[228:229]
	v_pk_mul_f32 v[160:161], v[44:45], v[160:161]
; __device__ __forceinline__ void phase_norm(PP P, int l, int which, int nsl, const float* fgate, float fscale, const Ids I) {
;     ...
;             if (nsl > 0 && row >= MTP && !(j == 1 && row == row0)) {
;                 const float* pp = (const float*)(P->ws + WS_R2) + (size_t)(row - MTP) * D + lane * 4; const float* gp = fgate + (size_t)mod_row(row) * 9216 + lane * 4;
; #pragma unroll
;                 for (int i = 0; i < 4; ++i) { f32x4 a = (f32x4){0.f, 0.f, 0.f, 0.f};
;                     for (int sl = 0; sl < nsl; ++sl) a += *(const f32x4*)(pp + (size_t)sl * MTS * D + 256 * i);
;                     v[j][i] += (*(const f32x4*)(gp + 256 * i) * fscale) * a;
;                     if (which != 3) *(f32x4*)(xb + (size_t)row * D + lane * 4 + 256 * i) = v[j][i]; } } }
	v_pk_mul_f32 v[158:159], v[46:47], v[158:159]
	v_pk_fma_f32 v[22:23], v[178:179], v[160:161], v[22:23]
	v_pk_fma_f32 v[20:21], v[176:177], v[158:159], v[20:21]
	global_store_dwordx4 v[10:11], v[20:23], off
	v_pk_mul_f32 v[164:165], v[44:45], v[164:165]
	v_pk_mul_f32 v[162:163], v[46:47], v[162:163]
	v_pk_fma_f32 v[14:15], v[182:183], v[164:165], v[14:15]
	v_pk_fma_f32 v[12:13], v[180:181], v[162:163], v[12:13]
	global_store_dwordx4 v[10:11], v[12:15], off offset:1024
	v_lshl_add_u64 v[16:17], v[70:71], 0, s[4:5]
	v_lshl_add_u64 v[24:25], v[72:73], 0, s[4:5]
	global_load_dwordx4 v[84:87], v[16:17], off
	global_load_dwordx4 v[188:191], v[24:25], off
	v_lshl_add_u64 v[16:17], v[16:17], 0, s[82:83]
	v_lshl_add_u64 v[24:25], v[24:25], 0, s[82:83]
	global_load_dwordx4 v[88:91], v[16:17], off
	global_load_dwordx4 v[192:195], v[24:25], off
	v_lshl_add_u64 v[16:17], v[16:17], 0, s[82:83]
	v_lshl_add_u64 v[24:25], v[24:25], 0, s[82:83]
	global_load_dwordx4 v[92:95], v[16:17], off
	global_load_dwordx4 v[196:199], v[24:25], off
	v_lshl_add_u64 v[16:17], v[16:17], 0, s[82:83]
	v_lshl_add_u64 v[24:25], v[24:25], 0, s[82:83]
	global_load_dwordx4 v[96:99], v[16:17], off
	global_load_dwordx4 v[200:203], v[24:25], off
	v_lshl_add_u64 v[16:17], v[16:17], 0, s[82:83]
	v_lshl_add_u64 v[24:25], v[24:25], 0, s[82:83]
	global_load_dwordx4 v[100:103], v[16:17], off
	global_load_dwordx4 v[204:207], v[24:25], off
	v_lshl_add_u64 v[16:17], v[16:17], 0, s[82:83]
	v_lshl_add_u64 v[24:25], v[24:25], 0, s[82:83]
	global_load_dwordx4 v[104:107], v[16:17], off
	global_load_dwordx4 v[208:211], v[24:25], off
	v_lshl_add_u64 v[16:17], v[16:17], 0, s[82:83]
	v_lshl_add_u64 v[24:25], v[24:25], 0, s[82:83]
	global_load_dwordx4 v[108:111], v[16:17], off
	global_load_dwordx4 v[212:215], v[24:25], off
	v_lshl_add_u64 v[16:17], v[16:17], 0, s[82:83]
	v_lshl_add_u64 v[24:25], v[24:25], 0, s[82:83]
	global_load_dwordx4 v[112:115], v[16:17], off
	global_load_dwordx4 v[216:219], v[24:25], off
	v_lshl_add_u64 v[16:17], v[16:17], 0, s[82:83]
	v_lshl_add_u64 v[24:25], v[24:25], 0, s[82:83]
	global_load_dwordx4 v[116:119], v[16:17], off
	global_load_dwordx4 v[220:223], v[24:25], off
	v_lshl_add_u64 v[16:17], v[16:17], 0, s[82:83]
	v_lshl_add_u64 v[24:25], v[24:25], 0, s[82:83]
	global_load_dwordx4 v[120:123], v[16:17], off
	global_load_dwordx4 v[224:227], v[24:25], off
	v_lshl_add_u64 v[16:17], v[16:17], 0, s[82:83]
	v_lshl_add_u64 v[24:25], v[24:25], 0, s[82:83]
	global_load_dwordx4 v[124:127], v[16:17], off
	global_load_dwordx4 v[228:231], v[24:25], off
	v_mov_b32_e32 v176, 0
	v_mov_b32_e32 v177, 0
	v_mov_b32_e32 v178, 0
	v_mov_b32_e32 v179, 0
	v_mov_b32_e32 v180, 0
	v_mov_b32_e32 v181, 0
	v_mov_b32_e32 v182, 0
	v_mov_b32_e32 v183, 0
	v_mov_b32_e32 v45, v44
	s_waitcnt vmcnt(0)
	v_pk_add_f32 v[178:179], v[178:179], v[86:87]
	v_pk_add_f32 v[176:177], v[176:177], v[84:85]
	v_pk_add_f32 v[182:183], v[182:183], v[190:191]
	v_pk_add_f32 v[180:181], v[180:181], v[188:189]
	v_pk_add_f32 v[178:179], v[178:179], v[90:91]
	v_pk_add_f32 v[176:177], v[176:177], v[88:89]
	v_pk_add_f32 v[182:183], v[182:183], v[194:195]
	v_pk_add_f32 v[180:181], v[180:181], v[192:193]
	v_pk_add_f32 v[178:179], v[178:179], v[94:95]
	v_pk_add_f32 v[176:177], v[176:177], v[92:93]
	v_pk_add_f32 v[182:183], v[182:183], v[198:199]
	v_pk_add_f32 v[180:181], v[180:181], v[196:197]
	v_pk_add_f32 v[178:179], v[178:179], v[98:99]
	v_pk_add_f32 v[176:177], v[176:177], v[96:97]
	v_pk_add_f32 v[182:183], v[182:183], v[202:203]
	v_pk_add_f32 v[180:181], v[180:181], v[200:201]
	v_pk_add_f32 v[178:179], v[178:179], v[102:103]
	v_pk_add_f32 v[176:177], v[176:177], v[100:101]
	v_pk_add_f32 v[182:183], v[182:183], v[206:207]
	v_pk_add_f32 v[180:181], v[180:181], v[204:205]
	v_pk_add_f32 v[178:179], v[178:179], v[106:107]
	v_pk_add_f32 v[176:177], v[176:177], v[104:105]
	v_pk_add_f32 v[182:183], v[182:183], v[210:211]
	v_pk_add_f32 v[180:181], v[180:181], v[208:209]
	v_pk_add_f32 v[178:179], v[178:179], v[110:111]
	v_pk_add_f32 v[176:177], v[176:177], v[108:109]
	v_pk_add_f32 v[182:183], v[182:183], v[214:215]
	v_pk_add_f32 v[180:181], v[180:181], v[212:213]
	v_pk_add_f32 v[178:179], v[178:179], v[114:115]
	v_pk_add_f32 v[176:177], v[176:177], v[112:113]
	v_pk_add_f32 v[182:183], v[182:183], v[218:219]
	v_pk_add_f32 v[180:181], v[180:181], v[216:217]
	v_pk_add_f32 v[178:179], v[178:179], v[118:119]
	v_pk_add_f32 v[176:177], v[176:177], v[116:117]
	v_pk_add_f32 v[182:183], v[182:183], v[222:223]
	v_pk_add_f32 v[180:181], v[180:181], v[220:221]
	v_pk_add_f32 v[178:179], v[178:179], v[122:123]
	v_pk_add_f32 v[176:177], v[176:177], v[120:121]
	v_pk_add_f32 v[182:183], v[182:183], v[226:227]
	v_pk_add_f32 v[180:181], v[180:181], v[224:225]
	v_pk_add_f32 v[178:179], v[178:179], v[126:127]
	v_pk_add_f32 v[176:177], v[176:177], v[124:125]
	v_pk_add_f32 v[182:183], v[182:183], v[230:231]
	v_pk_add_f32 v[180:181], v[180:181], v[228:229]
	v_pk_mul_f32 v[168:169], v[44:45], v[168:169]
	v_pk_mul_f32 v[166:167], v[46:47], v[166:167]
	v_pk_fma_f32 v[6:7], v[178:179], v[168:169], v[6:7]
	v_pk_fma_f32 v[4:5], v[176:177], v[166:167], v[4:5]
	global_store_dwordx4 v[10:11], v[4:7], off offset:2048
	v_pk_mul_f32 v[172:173], v[44:45], v[172:173]
	v_pk_mul_f32 v[170:171], v[46:47], v[170:171]
	v_pk_fma_f32 v[2:3], v[182:183], v[172:173], v[2:3]
	v_pk_fma_f32 v[0:1], v[180:181], v[170:171], v[0:1]
	global_store_dwordx4 v[10:11], v[0:3], off offset:3072
	s_branch .LBB0_557
; __device__ __forceinline__ void phase_norm(PP P, int l, int which, int nsl, const float* fgate, float fscale, const Ids I) {
;     ...
;             if (nsl > 0 && row >= MTP && !(j == 1 && row == row0)) {
;                 const float* pp = (const float*)(P->ws + WS_R2) + (size_t)(row - MTP) * D + lane * 4; const float* gp = fgate + (size_t)mod_row(row) * 9216 + lane * 4;
; #pragma unroll
;                 for (int i = 0; i < 4; ++i) { f32x4 a = (f32x4){0.f, 0.f, 0.f, 0.f};
;                     for (int sl = 0; sl < nsl; ++sl) a += *(const f32x4*)(pp + (size_t)sl * MTS * D + 256 * i);
;                     v[j][i] += (*(const f32x4*)(gp + 256 * i) * fscale) * a;
;                     if (which != 3) *(f32x4*)(xb + (size_t)row * D + lane * 4 + 256 * i) = v[j][i]; } } }
.Lnfold4:
	s_mov_b32 s17, s55
	s_lshl_b64 s[4:5], s[16:17], 12
	s_add_i32 s9, s8, 0xffffc000
	s_lshr_b32 s9, s9, 2
	s_add_i32 s9, s9, 8
	v_mad_u64_u32 v[8:9], s[18:19], s9, v184, v[52:53]
	s_mov_b32 s9, s55
	s_lshl_b64 s[18:19], s[8:9], 12
	v_lshl_add_u64 v[10:11], v[54:55], 0, s[18:19]
	v_lshl_add_u64 v[16:17], v[66:67], 0, s[4:5]
	v_lshl_add_u64 v[24:25], v[68:69], 0, s[4:5]
	global_load_dwordx4 v[158:161], v[8:9], off
	global_load_dwordx4 v[162:165], v[8:9], off offset:1024
	global_load_dwordx4 v[166:169], v[8:9], off offset:2048
	global_load_dwordx4 v[170:173], v[8:9], off offset:3072
	global_load_dwordx4 v[84:87], v[16:17], off
	global_load_dwordx4 v[188:191], v[24:25], off
	v_lshl_add_u64 v[16:17], v[16:17], 0, s[82:83]
	v_lshl_add_u64 v[24:25], v[24:25], 0, s[82:83]
	global_load_dwordx4 v[88:91], v[16:17], off
	global_load_dwordx4 v[192:195], v[24:25], off
	v_lshl_add_u64 v[16:17], v[16:17], 0, s[82:83]
	v_lshl_add_u64 v[24:25], v[24:25], 0, s[82:83]
	global_load_dwordx4 v[92:95], v[16:17], off
	global_load_dwordx4 v[196:199], v[24:25], off
	v_lshl_add_u64 v[16:17], v[16:17], 0, s[82:83]
	v_lshl_add_u64 v[24:25], v[24:25], 0, s[82:83]
	global_load_dwordx4 v[96:99], v[16:17], off
	global_load_dwordx4 v[200:203], v[24:25], off
	v_mov_b32_e32 v176, 0
	v_mov_b32_e32 v177, 0
	v_mov_b32_e32 v178, 0
	v_mov_b32_e32 v179, 0
	v_mov_b32_e32 v180, 0
	v_mov_b32_e32 v181, 0
	v_mov_b32_e32 v182, 0
	v_mov_b32_e32 v183, 0
	v_mov_b32_e32 v45, v44
	s_waitcnt vmcnt(0)
	v_pk_add_f32 v[178:179], v[178:179], v[86:87]
	v_pk_add_f32 v[176:177], v[176:177], v[84:85]
	v_pk_add_f32 v[182:183], v[182:183], v[190:191]
	v_pk_add_f32 v[180:181], v[180:181], v[188:189]
	v_pk_add_f32 v[178:179], v[178:179], v[90:91]
	v_pk_add_f32 v[176:177], v[176:177], v[88:89]
	v_pk_add_f32 v[182:183], v[182:183], v[194:195]
	v_pk_add_f32 v[180:181], v[180:181], v[192:193]
	v_pk_add_f32 v[178:179], v[178:179], v[94:95]
	v_pk_add_f32 v[176:177], v[176:177], v[92:93]
	v_pk_add_f32 v[182:183], v[182:183], v[198:199]
	v_pk_add_f32 v[180:181], v[180:181], v[196:197]
	v_pk_add_f32 v[178:179], v[178:179], v[98:99]
	v_pk_add_f32 v[176:177], v[176:177], v[96:97]
	v_pk_add_f32 v[182:183], v[182:183], v[202:203]
	v_pk_add_f32 v[180:181], v[180:181], v[200:201]
	v_pk_mul_f32 v[160:161], v[44:45], v[160:161]
	v_pk_mul_f32 v[158:159], v[46:47], v[158:159]
	v_pk_fma_f32 v[22:23], v[178:179], v[160:161], v[22:23]
	v_pk_fma_f32 v[20:21], v[176:177], v[158:159], v[20:21]
	global_store_dwordx4 v[10:11], v[20:23], off
	v_pk_mul_f32 v[164:165], v[44:45], v[164:165]
	v_pk_mul_f32 v[162:163], v[46:47], v[162:163]
	v_pk_fma_f32 v[14:15], v[182:183], v[164:165], v[14:15]
	v_pk_fma_f32 v[12:13], v[180:181], v[162:163], v[12:13]
	global_store_dwordx4 v[10:11], v[12:15], off offset:1024
	v_lshl_add_u64 v[16:17], v[70:71], 0, s[4:5]
	v_lshl_add_u64 v[24:25], v[72:73], 0, s[4:5]
	global_load_dwordx4 v[84:87], v[16:17], off
	global_load_dwordx4 v[188:191], v[24:25], off
	v_lshl_add_u64 v[16:17], v[16:17], 0, s[82:83]
	v_lshl_add_u64 v[24:25], v[24:25], 0, s[82:83]
	global_load_dwordx4 v[88:91], v[16:17], off
	global_load_dwordx4 v[192:195], v[24:25], off
	v_lshl_add_u64 v[16:17], v[16:17], 0, s[82:83]
	v_lshl_add_u64 v[24:25], v[24:25], 0, s[82:83]
	global_load_dwordx4 v[92:95], v[16:17], off
	global_load_dwordx4 v[196:199], v[24:25], off
	v_lshl_add_u64 v[16:17], v[16:17], 0, s[82:83]
	v_lshl_add_u64 v[24:25], v[24:25], 0, s[82:83]
	global_load_dwordx4 v[96:99], v[16:17], off
	global_load_dwordx4 v[200:203], v[24:25], off
	v_mov_b32_e32 v176, 0
	v_mov_b32_e32 v177, 0
	v_mov_b32_e32 v178, 0
	v_mov_b32_e32 v179, 0
	v_mov_b32_e32 v180, 0
	v_mov_b32_e32 v181, 0
	v_mov_b32_e32 v182, 0
	v_mov_b32_e32 v183, 0
	v_mov_b32_e32 v45, v44
	s_waitcnt vmcnt(0)
	v_pk_add_f32 v[178:179], v[178:179], v[86:87]
	v_pk_add_f32 v[176:177], v[176:177], v[84:85]
	v_pk_add_f32 v[182:183], v[182:183], v[190:191]
	v_pk_add_f32 v[180:181], v[180:181], v[188:189]
	v_pk_add_f32 v[178:179], v[178:179], v[90:91]
	v_pk_add_f32 v[176:177], v[176:177], v[88:89]
	v_pk_add_f32 v[182:183], v[182:183], v[194:195]
	v_pk_add_f32 v[180:181], v[180:181], v[192:193]
	v_pk_add_f32 v[178:179], v[178:179], v[94:95]
	v_pk_add_f32 v[176:177], v[176:177], v[92:93]
	v_pk_add_f32 v[182:183], v[182:183], v[198:199]
	v_pk_add_f32 v[180:181], v[180:181], v[196:197]
	v_pk_add_f32 v[178:179], v[178:179], v[98:99]
	v_pk_add_f32 v[176:177], v[176:177], v[96:97]
	v_pk_add_f32 v[182:183], v[182:183], v[202:203]
	v_pk_add_f32 v[180:181], v[180:181], v[200:201]
	v_pk_mul_f32 v[168:169], v[44:45], v[168:169]
	v_pk_mul_f32 v[166:167], v[46:47], v[166:167]
	v_pk_fma_f32 v[6:7], v[178:179], v[168:169], v[6:7]
	v_pk_fma_f32 v[4:5], v[176:177], v[166:167], v[4:5]
	global_store_dwordx4 v[10:11], v[4:7], off offset:2048
	v_pk_mul_f32 v[172:173], v[44:45], v[172:173]
	v_pk_mul_f32 v[170:171], v[46:47], v[170:171]
	v_pk_fma_f32 v[2:3], v[182:183], v[172:173], v[2:3]
	v_pk_fma_f32 v[0:1], v[180:181], v[170:171], v[0:1]
	global_store_dwordx4 v[10:11], v[0:3], off offset:3072
	s_branch .LBB0_557
